# P0 row loop and mla_prep loop: loop-invariant kernarg pointer loads hoisted out of the loops (s_load + wait per row -> s_mov)
# baseline (speedup 1.0000x reference)
; __device__ __forceinline__ void mla_prep(const Args& a, int vcu, int G, int lane, int wave) {
;     int z = 0; asm volatile("" : "+s"(z));
;     unsigned char* ws = (unsigned char*)a.in[I_WS + z];
;     const int gw = vcu * NWAVES + wave, NGW = G * NWAVES;
;     const bf16* Z = (const bf16*)(ws + WS_Z);
;     const float* cosT = (const float*)(ws + WS_ROPE); const float* sinT = cosT + ROPE_TAB;
;     const float* qn = (const float*)a.in[I_QNORM + z]; const float* kn = (const float*)a.in[I_KVNORM + z];
;     for (int m0 = gw; m0 < MT; m0 += 4 * NGW) {
.LBB0_867:
	s_mov_b32 s2, 0
	s_ashr_i32 s3, s2, 31
	s_lshl_b64 s[2:3], s[2:3], 3
	s_add_u32 s6, s86, s2
	s_addc_u32 s7, s87, s3
	s_load_dwordx2 s[8:9], s[6:7], 0x150
	s_lshl_b32 s2, s34, 3
	s_add_i32 s4, s2, s93
	s_lshl_b32 s68, s33, 3
	v_and_b32_e32 v4, 63, v152
	s_waitcnt lgkmcnt(0)
	s_add_u32 s69, s8, 0x11d00000
	s_addc_u32 s70, s9, 0
	s_cmpk_gt_i32 s4, 0x40ff
	s_mov_b32 s11, 0
	s_cbranch_scc1 .LBB0_937
	s_load_dwordx2 s[18:19], s[6:7], 0xc0
	s_load_dwordx2 s[2:3], s[6:7], 0xd8
	s_add_u32 s12, s8, 0x3d00000
	s_addc_u32 s13, s9, 0
	v_mov_b32_e32 v7, 0
	v_lshlrev_b32_e32 v6, 4, v4
	s_add_u32 s14, s8, 0x3d80040
	s_waitcnt lgkmcnt(0)
	v_lshl_add_u64 v[10:11], s[2:3], 0, v[6:7]
	v_lshlrev_b32_e32 v6, 3, v4
	v_lshlrev_b32_e32 v36, 2, v4
	v_mov_b32_e32 v37, v7
	s_addc_u32 s15, s9, 0
	v_lshl_add_u64 v[14:15], s[18:19], 0, v[6:7]
	v_lshl_add_u64 v[16:17], s[8:9], 0, v[36:37]
	s_mov_b64 s[18:19], 0x1c800000
	v_lshlrev_b32_e32 v26, 1, v4
	v_mov_b32_e32 v27, v7
	s_add_i32 s30, s4, s68
	s_lshl_b32 s16, s33, 5
	v_lshl_add_u64 v[16:17], v[16:17], 0, s[18:19]
	v_lshl_add_u64 v[18:19], s[8:9], 0, v[26:27]
	s_mov_b64 s[18:19], 0x1de00000
	s_ashr_i32 s31, s30, 31
	v_lshl_add_u64 v[18:19], v[18:19], 0, s[18:19]
	s_lshl_b64 s[18:19], s[30:31], 6
	s_ashr_i32 s17, s16, 31
	s_lshl_b64 s[24:25], s[30:31], 9
	v_lshl_add_u64 v[20:21], s[18:19], 0, v[26:27]
	s_lshl_b64 s[18:19], s[16:17], 6
	s_lshl_b64 s[22:23], s[16:17], 7
	v_or_b32_e32 v22, s24, v6
	v_mov_b32_e32 v23, s25
	s_lshl_b64 s[24:25], s[16:17], 9
	s_lshl_b64 s[28:29], s[16:17], 10
	s_mul_hi_i32 s5, s30, 0x300
	s_mul_i32 s17, s30, 0x300
	v_or_b32_e32 v24, s17, v36
	v_mov_b32_e32 v25, s5
	s_lshl_b32 s5, s34, 7
	s_lshl_b32 s17, s93, 4
	s_add_i32 s17, s5, s17
	s_ashr_i32 s5, s4, 31
	s_lshl_b64 s[38:39], s[4:5], 9
	v_lshl_add_u64 v[0:1], s[8:9], 0, v[6:7]
	s_mov_b64 s[36:37], 0x1d500000
	s_lshl_b64 s[34:35], s[4:5], 6
	v_or_b32_e32 v28, s38, v6
	v_mov_b32_e32 v29, s39
	v_lshl_add_u64 v[12:13], v[0:1], 0, s[36:37]
	v_lshl_add_u64 v[22:23], v[22:23], 0, s[36:37]
	v_lshl_add_u64 v[26:27], s[34:35], 0, v[26:27]
	s_lshl_b64 s[34:35], s[4:5], 7
	v_lshl_add_u64 v[28:29], v[28:29], 0, s[36:37]
	s_lshl_b64 s[36:37], s[4:5], 10
	s_mul_hi_i32 s5, s4, 0x300
	v_mov_b32_e32 v31, s5
	s_mul_hi_i32 s5, s4, 0x2a00
	s_mul_i32 s42, s4, 0x2a00
	v_and_b32_e32 v8, 15, v152
	v_or_b32_e32 v0, 64, v4
	v_or_b32_e32 v2, 0x80, v4
	s_mul_i32 s38, s4, 0x300
	v_or_b32_e32 v34, s42, v6
	v_mov_b32_e32 v35, s5
	s_mov_b64 s[40:41], 0x11d01700
	v_cmp_gt_u32_e64 s[2:3], 16, v4
	s_add_i32 s10, s4, 0xffffc000
	s_lshl_b32 s71, s33, 4
	s_mul_i32 s72, s33, 24
	s_lshl_b64 s[20:21], s[30:31], 7
	s_lshl_b64 s[26:27], s[30:31], 10
	s_mul_i32 s30, s33, 0x6000
	s_mul_hi_i32 s31, s16, 0x300
	s_lshl_b32 s73, s33, 9
	v_or_b32_e32 v30, s38, v36
	v_lshl_or_b32 v32, v8, 1, s42
	v_mov_b32_e32 v33, s5
	s_mul_i32 s38, s33, 0x54000
	s_mul_hi_i32 s39, s16, 0x2a00
	v_lshl_add_u64 v[34:35], v[34:35], 0, s[40:41]
	v_or_b32_e32 v36, s42, v36
	v_mov_b32_e32 v37, s5
	s_mov_b64 s[40:41], 0x5080000
	s_mov_b64 s[42:43], 0x4080000
	s_mov_b32 s5, 0x11d01000
	v_lshlrev_b32_e32 v5, 2, v4
	v_lshlrev_b32_e32 v9, 2, v0
	v_lshlrev_b32_e32 v46, 2, v2
	v_lshlrev_b32_e32 v6, 3, v4
	s_movk_i32 s33, 0x1000
	v_lshlrev_b32_e32 v38, 1, v8
	v_mov_b32_e32 v47, 0x358637bd
	s_mov_b32 s74, 0x1c800000
	v_mov_b32_e32 v39, v7
	v_mov_b32_e32 v48, 0x300
	s_load_dwordx2 s[98:99], s[6:7], 0x148
	s_waitcnt lgkmcnt(0)
	s_branch .LBB0_871

; __device__ __forceinline__ float bf2f(bf16 v) { return __uint_as_float((unsigned)v << 16); }
; __device__ __forceinline__ void mla_prep(const Args& a, int vcu, int G, int lane, int wave) {
;     ...
;     for (int m0 = gw; m0 < MT; m0 += 4 * NGW) {
;         unsigned qw[4][3]; u32x2 kw4[4]; float x1[4], x2[4], cs[4], sn4[4];
; #pragma unroll
;         for (int qq = 0; qq < 4; ++qq) { const int m = m0 + qq * NGW, mm = m < MT ? m : m0; const bf16* zr = Z + (size_t)mm * ZW;
; #pragma unroll
;             for (int j = 0; j < 3; ++j) qw[qq][j] = ((const unsigned*)(zr + Z_CQ))[lane + 64 * j];
;             kw4[qq] = ((const u32x2*)(zr + Z_KV))[lane];
;             const int pos = mm < MP ? (mm & (SEQ - 1)) : SEQ, l16 = lane & 15;
;             x1[qq] = bf2f(zr[Z_KR + l16]); x2[qq] = bf2f(zr[Z_KR + 16 + l16]); cs[qq] = cosT[pos * 16 + l16]; sn4[qq] = sinT[pos * 16 + l16]; }
.LBB0_871:
	s_add_i32 s47, s10, 0x4000
	s_cmpk_gt_i32 s47, 0x3fff
	s_cselect_b64 s[60:61], -1, 0
	s_and_b32 s44, s17, 0x1fff0
	s_cmpk_lt_i32 s47, 0x4000
	s_cselect_b32 s49, s44, 0x20000
	s_add_i32 s54, s68, s10
	s_add_i32 s45, s54, 0x4000
	s_cmpk_lt_i32 s45, 0x4100
	s_cselect_b64 s[58:59], -1, 0
	s_and_b64 s[50:51], s[58:59], exec
	s_cselect_b32 s44, s45, s47
	s_mul_i32 s48, s44, 0x2a00
	s_mul_hi_i32 s46, s44, 0x2a00
	s_add_u32 s50, s69, s48
	s_addc_u32 s51, s70, s46
	v_lshl_add_u64 v[0:1], s[50:51], 0, v[6:7]
	v_add_co_u32_e32 v0, vcc, s33, v0
	v_lshl_add_u64 v[42:43], s[8:9], 0, v[36:37]
	s_nop 0
	v_addc_co_u32_e32 v1, vcc, 0, v1, vcc
	v_lshl_add_u64 v[40:41], s[8:9], 0, v[34:35]
	v_add_co_u32_e32 v42, vcc, s5, v42
	s_add_u32 s62, s50, 0x1400
	s_nop 0
	v_addc_co_u32_e32 v43, vcc, 0, v43, vcc
	global_load_dwordx2 v[74:75], v[40:41], off
	global_load_dword v49, v[42:43], off offset:1536
	global_load_dword v50, v[42:43], off offset:1280
	global_load_dword v51, v[42:43], off offset:1024
	s_addc_u32 s63, s51, 0
	s_lshl_b32 s46, s44, 4
	s_and_b32 s46, s46, 0x1fff0
	s_cmpk_lt_i32 s44, 0x4000
	s_cselect_b32 s53, s46, 0x20000
	s_add_i32 s52, s71, s10
	s_add_i32 s48, s52, 0x4000
	s_cmpk_lt_i32 s48, 0x4100
	s_cselect_b64 s[56:57], -1, 0
	v_lshl_add_u64 v[2:3], s[50:51], 0, v[38:39]
	s_and_b64 s[50:51], s[56:57], exec
	s_cselect_b32 s44, s48, s47
	s_mul_i32 s50, s44, 0x2a00
	s_mul_hi_i32 s46, s44, 0x2a00
	s_add_u32 s50, s69, s50
	s_addc_u32 s51, s70, s46
	s_add_u32 s64, s50, 0x1400
	v_add_co_u32_e32 v2, vcc, s33, v2
	s_addc_u32 s65, s51, 0
	s_lshl_b32 s46, s44, 4
	v_addc_co_u32_e32 v3, vcc, 0, v3, vcc
	v_lshl_add_u64 v[40:41], s[50:51], 0, v[6:7]
	s_and_b32 s46, s46, 0x1fff0
	v_add_co_u32_e32 v40, vcc, s33, v40
	s_cmpk_lt_i32 s44, 0x4000
	s_nop 0
	v_addc_co_u32_e32 v41, vcc, 0, v41, vcc
	v_lshl_add_u64 v[42:43], s[50:51], 0, v[38:39]
	s_cselect_b32 s44, s46, 0x20000
	s_add_i32 s46, s72, s10
	v_add_co_u32_e32 v44, vcc, s33, v42
	v_or_b32_e32 v42, s44, v8
	s_add_i32 s44, s46, 0x4000
	s_cmpk_lt_i32 s44, 0x4100
	s_cselect_b64 s[50:51], -1, 0
	s_and_b64 s[66:67], s[50:51], exec
	s_cselect_b32 s55, s44, s47
	v_addc_co_u32_e32 v45, vcc, 0, v43, vcc
	v_lshlrev_b32_e32 v52, 2, v42
	global_load_dwordx2 v[70:71], v[14:15], off
	global_load_dwordx2 v[42:43], v[40:41], off offset:1792
	global_load_ushort v58, v[44:45], off offset:2304
	global_load_ushort v59, v[44:45], off offset:2336
	global_load_dword v57, v52, s[12:13]
	global_load_dword v56, v52, s[14:15]
	s_mul_i32 s66, s55, 0x2a00
	s_mul_hi_i32 s67, s55, 0x2a00
	s_add_u32 s66, s69, s66
	s_addc_u32 s67, s70, s67
	s_add_u32 s76, s66, 0x1400
	s_addc_u32 s77, s67, 0
	global_load_dword v68, v5, s[62:63]
	global_load_dword v67, v9, s[62:63]
	global_load_dword v60, v5, s[64:65]
	global_load_dword v53, v5, s[76:77]
	global_load_dword v69, v46, s[62:63]
	global_load_dwordx2 v[44:45], v[0:1], off offset:1792
	global_load_ushort v63, v[2:3], off offset:2304
	global_load_ushort v64, v[2:3], off offset:2336
	global_load_dword v62, v9, s[64:65]
	global_load_dword v61, v46, s[64:65]
	global_load_dword v54, v46, s[76:77]
	global_load_dword v55, v9, s[76:77]
	s_lshl_b32 s62, s55, 4
	s_and_b32 s62, s62, 0x1fff0
	s_cmpk_lt_i32 s55, 0x4000
	s_cselect_b32 s55, s62, 0x20000
	v_or_b32_e32 v40, s55, v8
	global_load_dwordx2 v[90:91], v[14:15], off
	global_load_dwordx2 v[92:93], v[14:15], off offset:512
	global_load_dwordx2 v[94:95], v[14:15], off offset:1024
	global_load_dwordx4 v[96:99], v[10:11], off
	s_waitcnt vmcnt(0)
	v_lshlrev_b32_e32 v65, 2, v40
	v_lshl_add_u64 v[0:1], s[66:67], 0, v[6:7]
	v_add_co_u32_e32 v0, vcc, s33, v0
	v_lshl_add_u64 v[2:3], s[66:67], 0, v[38:39]
	s_nop 0
	v_addc_co_u32_e32 v1, vcc, 0, v1, vcc
	v_add_co_u32_e32 v2, vcc, s33, v2
	s_mov_b64 s[64:65], -1
	s_nop 0
	v_addc_co_u32_e32 v3, vcc, 0, v3, vcc
	s_mov_b64 s[66:67], 0
	s_waitcnt vmcnt(0)
; __device__ __forceinline__ float bflo(unsigned w) { return __uint_as_float(w << 16); }
; __device__ __forceinline__ float bfhi(unsigned w) { return __uint_as_float(w & 0xffff0000u); }
; __device__ __forceinline__ unsigned pk2(float lo, float hi) { f32x2 v = {lo, hi}; bf16x2_t b = __builtin_convertvector(v, bf16x2_t); return __builtin_bit_cast(unsigned, b); }
; __device__ __forceinline__ void mla_prep(const Args& a, int vcu, int G, int lane, int wave) {
;     ...
;         for (int qq = 0; qq < 4; ++qq) { const int m = m0 + qq * NGW; if (m >= MT) break;
;             float q[6]; float s = 0.f;
; #pragma unroll
;             for (int j = 0; j < 3; ++j) { const unsigned w = qw[qq][j]; q[2 * j] = bflo(w); q[2 * j + 1] = bfhi(w); s += q[2 * j] * q[2 * j] + q[2 * j + 1] * q[2 * j + 1]; }
;             const float rq = __builtin_amdgcn_rsqf(wave_sum(s) * (1.f / QL) + EPS);
; #pragma unroll
;             for (int j = 0; j < 3; ++j) { const f32x2 g = ((const f32x2*)qn)[lane + 64 * j]; ((unsigned*)((bf16*)(ws + WS_CQ) + (size_t)m * QL))[lane + 64 * j] = pk2(q[2 * j] * rq * g.x, q[2 * j + 1] * rq * g.y); }
;             const u32x2 kw = kw4[qq];
;             f32x4 kv = {bflo(kw.x), bfhi(kw.x), bflo(kw.y), bfhi(kw.y)};
;             const float rk = __builtin_amdgcn_rsqf(wave_sum((kv.x * kv.x + kv.y * kv.y) + (kv.z * kv.z + kv.w * kv.w)) * (1.f / KVL) + EPS);
;             kv = kv * rk * ((const f32x4*)kn)[lane];
;             { u32x2 o; o.x = pk2(kv.x, kv.y); o.y = pk2(kv.z, kv.w); ((u32x2*)((bf16*)(ws + WS_CKV) + (size_t)m * KVL))[lane] = o; }
;             if (m < MP) ((f32x4*)((float*)a.in[I_OUT + z] + O_CKV_P + (size_t)m * KVL))[lane] = kv;
;             else if (m < MP + NS) ((f32x4*)((float*)a.in[I_OUT + z] + O_CKV_S + (size_t)(m - MP) * KVL))[lane] = kv;
	v_lshlrev_b32_e32 v78, 16, v49
	v_lshlrev_b32_e32 v76, 16, v50
	v_lshlrev_b32_e32 v72, 16, v51
	v_and_b32_e32 v73, 0xffff0000, v51
	v_and_b32_e32 v77, 0xffff0000, v50
	v_and_b32_e32 v79, 0xffff0000, v49
	v_pk_mul_f32 v[40:41], v[72:73], v[72:73]
	v_pk_mul_f32 v[50:51], v[76:77], v[76:77]
	v_pk_mul_f32 v[80:81], v[78:79], v[78:79]
	v_add_f32_e32 v40, v40, v41
	v_add_f32_e32 v41, v50, v51
	v_add_f32_e32 v40, v41, v40
	v_add_f32_e32 v41, v80, v81
	v_add_f32_e32 v40, v41, v40
	s_nop 1
	v_add_f32_dpp v40, v40, v40 quad_perm:[1,0,3,2] row_mask:0xf bank_mask:0xf bound_ctrl:1
	s_nop 1
	v_add_f32_dpp v40, v40, v40 quad_perm:[2,3,0,1] row_mask:0xf bank_mask:0xf bound_ctrl:1
	s_nop 1
	v_add_f32_dpp v40, v40, v40 row_half_mirror row_mask:0xf bank_mask:0xf bound_ctrl:1
	s_nop 1
	v_add_f32_dpp v40, v40, v40 row_mirror row_mask:0xf bank_mask:0xf bound_ctrl:1
	v_mov_b32_e32 v41, v40
	s_nop 1
	v_permlane16_swap_b32_e32 v40, v41
	v_add_f32_e32 v40, v40, v41
	v_mov_b32_e32 v41, v40
	s_nop 1
	v_permlane32_swap_b32_e32 v40, v41
	v_add_f32_e32 v40, v40, v41
	v_fmamk_f32 v40, v40, 0x3b2aaaab, v47
	v_rsq_f32_e32 v66, v40
	global_load_dwordx2 v[40:41], v[0:1], off offset:1792
	global_load_ushort v51, v[2:3], off offset:2304
	global_load_ushort v52, v[2:3], off offset:2336
	global_load_dword v50, v65, s[12:13]
	global_load_dword v49, v65, s[14:15]
	v_lshl_add_u64 v[0:1], s[8:9], 0, v[30:31]
	v_add_co_u32_e32 v0, vcc, s74, v0
	v_or_b32_e32 v65, s49, v8
	s_nop 0
	v_addc_co_u32_e32 v1, vcc, 0, v1, vcc
	v_lshlrev_b32_e32 v65, 2, v65
	v_pk_mul_f32 v[2:3], v[66:67], v[72:73] op_sel_hi:[0,1]
	v_pk_mul_f32 v[2:3], v[70:71], v[2:3]
	v_pk_mul_f32 v[70:71], v[66:67], v[76:77] op_sel_hi:[0,1]
	v_cvt_pk_bf16_f32 v2, v2, v3
	global_store_dword v[0:1], v2, off
	s_nop 0
	v_mov_b64_e32 v[2:3], v[92:93]
	v_pk_mul_f32 v[72:73], v[66:67], v[78:79] op_sel_hi:[0,1]
	v_lshlrev_b32_e32 v78, 16, v74
	v_and_b32_e32 v79, 0xffff0000, v74
	v_lshlrev_b32_e32 v74, 16, v75
	v_and_b32_e32 v75, 0xffff0000, v75
	v_mul_f32_e32 v80, v79, v79
	v_mul_f32_e32 v81, v75, v75
	v_fmac_f32_e32 v80, v78, v78
	v_fmac_f32_e32 v81, v74, v74
	v_add_f32_e32 v80, v80, v81
	v_lshl_add_u64 v[76:77], s[8:9], 0, v[28:29]
	v_pk_mul_f32 v[2:3], v[2:3], v[70:71]
	s_nop 0
	v_cvt_pk_bf16_f32 v2, v2, v3
	global_store_dword v[0:1], v2, off offset:256
	s_nop 0
	v_mov_b64_e32 v[2:3], v[94:95]
	v_lshl_add_u64 v[70:71], s[8:9], 0, v[32:33]
	v_add_co_u32_e32 v70, vcc, s5, v70
	v_add_f32_dpp v80, v80, v80 quad_perm:[1,0,3,2] row_mask:0xf bank_mask:0xf bound_ctrl:1
	s_nop 0
	v_addc_co_u32_e32 v71, vcc, 0, v71, vcc
	v_add_f32_dpp v80, v80, v80 quad_perm:[2,3,0,1] row_mask:0xf bank_mask:0xf bound_ctrl:1
	s_and_b64 vcc, exec, s[60:61]
	v_pk_mul_f32 v[2:3], v[2:3], v[72:73]
	s_nop 0
	v_cvt_pk_bf16_f32 v2, v2, v3
	global_store_dword v[0:1], v2, off offset:512
	s_nop 0
	v_mov_b64_e32 v[0:1], v[96:97]
	v_mov_b64_e32 v[2:3], v[98:99]
	s_nop 0
	global_load_ushort v72, v[70:71], off offset:2304
	global_load_ushort v73, v[70:71], off offset:2336
	s_nop 0
	global_load_dword v71, v65, s[12:13]
	global_load_dword v70, v65, s[14:15]
	v_or_b32_e32 v65, s53, v8
	v_lshlrev_b32_e32 v65, 2, v65
	global_load_dword v66, v65, s[12:13]
	s_nop 0
	global_load_dword v65, v65, s[14:15]
	v_add_f32_dpp v80, v80, v80 row_half_mirror row_mask:0xf bank_mask:0xf bound_ctrl:1
	s_nop 1
	v_add_f32_dpp v80, v80, v80 row_mirror row_mask:0xf bank_mask:0xf bound_ctrl:1
	v_mov_b32_e32 v81, v80
	s_nop 1
	v_permlane16_swap_b32_e32 v80, v81
	v_add_f32_e32 v80, v80, v81
	v_mov_b32_e32 v81, v80
	s_nop 1
	v_permlane32_swap_b32_e32 v80, v81
	v_add_f32_e32 v80, v80, v81
	v_fmamk_f32 v80, v80, 0x3b800000, v47
	v_rsq_f32_e32 v80, v80
	s_nop 0
	v_pk_mul_f32 v[74:75], v[74:75], v[80:81] op_sel_hi:[1,0]
	v_pk_mul_f32 v[78:79], v[78:79], v[80:81] op_sel_hi:[1,0]
	v_pk_mul_f32 v[2:3], v[2:3], v[74:75]
	v_pk_mul_f32 v[0:1], v[0:1], v[78:79]
	v_cvt_pk_bf16_f32 v75, v2, v3
	v_cvt_pk_bf16_f32 v74, v0, v1
	global_store_dwordx2 v[76:77], v[74:75], off
	s_cbranch_vccz .LBB0_874
	s_mov_b64 s[64:65], 0
	s_cmpk_lt_u32 s47, 0x4080
	s_cbranch_scc0 .LBB0_874
	s_mov_b64 s[62:63], s[98:99]
	s_lshl_b64 s[66:67], s[10:11], 10
	s_waitcnt lgkmcnt(0)
	s_add_u32 s49, s62, s66
	s_addc_u32 s53, s63, s67
	s_add_u32 s62, s49, 0x528a000
	s_addc_u32 s63, s53, 0
	s_mov_b64 s[66:67], -1
.LBB0_874:
	s_and_b64 vcc, exec, s[64:65]
	s_cbranch_vccz .LBB0_876
	s_mov_b64 s[62:63], s[98:99]
	s_mov_b64 s[66:67], -1
	s_waitcnt lgkmcnt(0)
	s_add_u32 s49, s62, s36
	s_addc_u32 s53, s63, s37
	s_add_u32 s62, s49, s42
	s_addc_u32 s63, s53, s43

; __device__ __forceinline__ bf16 f2bf(float f) { return (bf16)(pk2(f, 0.f) & 0xffffu); }
; __device__ __forceinline__ void mla_prep(const Args& a, int vcu, int G, int lane, int wave) {
;     ...
;             if (lane < 16) {
;                 const float o1 = x1[qq] * cs[qq] - x2[qq] * sn4[qq], o2 = x1[qq] * sn4[qq] + x2[qq] * cs[qq];
;                 bf16* kr = (bf16*)(ws + WS_KR) + (size_t)m * ROPE;
;                 kr[lane] = f2bf(o1); kr[16 + lane] = f2bf(o2);
;                 float* ko = m < MP ? (float*)a.in[I_OUT + z] + O_KR_P + (size_t)m * ROPE : (m < MP + NS ? (float*)a.in[I_OUT + z] + O_KR_S + (size_t)(m - MP) * ROPE : nullptr);
;                 if (ko) { ko[lane] = o1; ko[16 + lane] = o2; }
.LBB0_878:
	s_and_saveexec_b64 s[62:63], s[2:3]
	s_cbranch_execz .LBB0_886
	s_waitcnt vmcnt(5)
	v_lshlrev_b32_e32 v1, 16, v73
	v_lshlrev_b32_e32 v2, 16, v72
	s_waitcnt vmcnt(3)
	v_mul_f32_e32 v0, v70, v1
	v_mul_f32_e32 v1, v71, v1
	v_fma_f32 v0, v71, v2, -v0
	v_fmac_f32_e32 v1, v70, v2
	v_lshl_add_u64 v[2:3], s[8:9], 0, v[26:27]
	v_add_co_u32_e32 v2, vcc, 0x1de00000, v2
	v_cvt_pk_bf16_f32 v70, v0, s0
	s_nop 0
	v_addc_co_u32_e32 v3, vcc, 0, v3, vcc
	global_store_short v[2:3], v70, off
	v_cvt_pk_bf16_f32 v70, v1, s0
	s_mov_b64 s[64:65], -1
	s_and_b64 vcc, exec, s[60:61]
	global_store_short v[2:3], v70, off offset:32
	s_cbranch_vccz .LBB0_882
	s_mov_b64 s[64:65], 0
	s_cmpk_gt_u32 s47, 0x407f
	s_mov_b64 s[60:61], 0
	s_cbranch_scc1 .LBB0_882
	s_mov_b64 s[60:61], s[98:99]
	s_lshl_b64 s[66:67], s[10:11], 7
	s_waitcnt lgkmcnt(0)
	s_add_u32 s47, s60, s66
	s_addc_u32 s49, s61, s67
	s_add_u32 s60, s47, 0x52aa000
	s_addc_u32 s61, s49, 0
.LBB0_882:
	s_andn2_b64 vcc, exec, s[64:65]
	s_cbranch_vccnz .LBB0_884
	s_mov_b64 s[60:61], s[98:99]
	s_waitcnt lgkmcnt(0)
	s_add_u32 s47, s60, s34
	s_addc_u32 s49, s61, s35
	s_add_u32 s60, s47, s40
	s_addc_u32 s61, s49, s41

; __device__ __forceinline__ float bflo(unsigned w) { return __uint_as_float(w << 16); }
; __device__ __forceinline__ float bfhi(unsigned w) { return __uint_as_float(w & 0xffff0000u); }
; __device__ __forceinline__ unsigned pk2(float lo, float hi) { f32x2 v = {lo, hi}; bf16x2_t b = __builtin_convertvector(v, bf16x2_t); return __builtin_bit_cast(unsigned, b); }
; __device__ __forceinline__ void mla_prep(const Args& a, int vcu, int G, int lane, int wave) {
;     ...
;         for (int qq = 0; qq < 4; ++qq) { const int m = m0 + qq * NGW; if (m >= MT) break;
;             float q[6]; float s = 0.f;
; #pragma unroll
;             for (int j = 0; j < 3; ++j) { const unsigned w = qw[qq][j]; q[2 * j] = bflo(w); q[2 * j + 1] = bfhi(w); s += q[2 * j] * q[2 * j] + q[2 * j + 1] * q[2 * j + 1]; }
;             const float rq = __builtin_amdgcn_rsqf(wave_sum(s) * (1.f / QL) + EPS);
; #pragma unroll
;             for (int j = 0; j < 3; ++j) { const f32x2 g = ((const f32x2*)qn)[lane + 64 * j]; ((unsigned*)((bf16*)(ws + WS_CQ) + (size_t)m * QL))[lane + 64 * j] = pk2(q[2 * j] * rq * g.x, q[2 * j + 1] * rq * g.y); }
;             const u32x2 kw = kw4[qq];
;             f32x4 kv = {bflo(kw.x), bfhi(kw.x), bflo(kw.y), bfhi(kw.y)};
;             const float rk = __builtin_amdgcn_rsqf(wave_sum((kv.x * kv.x + kv.y * kv.y) + (kv.z * kv.z + kv.w * kv.w)) * (1.f / KVL) + EPS);
;             kv = kv * rk * ((const f32x4*)kn)[lane];
;             { u32x2 o; o.x = pk2(kv.x, kv.y); o.y = pk2(kv.z, kv.w); ((u32x2*)((bf16*)(ws + WS_CKV) + (size_t)m * KVL))[lane] = o; }
;             if (m < MP) ((f32x4*)((float*)a.in[I_OUT + z] + O_CKV_P + (size_t)m * KVL))[lane] = kv;
;             else if (m < MP + NS) ((f32x4*)((float*)a.in[I_OUT + z] + O_CKV_S + (size_t)(m - MP) * KVL))[lane] = kv;
.LBB0_886:
	s_or_b64 exec, exec, s[62:63]
	s_andn2_b64 vcc, exec, s[58:59]
	s_cbranch_vccnz .LBB0_870
	v_mov_b64_e32 v[0:1], v[90:91]
	v_lshlrev_b32_e32 v2, 16, v68
	v_and_b32_e32 v3, 0xffff0000, v68
	s_waitcnt vmcnt(3)
	v_lshlrev_b32_e32 v70, 16, v67
	v_and_b32_e32 v71, 0xffff0000, v67
	v_lshlrev_b32_e32 v68, 16, v69
	v_and_b32_e32 v69, 0xffff0000, v69
	v_pk_mul_f32 v[74:75], v[2:3], v[2:3]
	v_pk_mul_f32 v[76:77], v[70:71], v[70:71]
	v_pk_mul_f32 v[78:79], v[68:69], v[68:69]
	v_add_f32_e32 v67, v76, v77
	v_add_f32_e32 v74, v74, v75
	v_add_f32_e32 v75, v78, v79
	v_add_f32_e32 v67, v74, v67
	v_add_f32_e32 v67, v67, v75
	v_lshl_add_u64 v[72:73], s[8:9], 0, v[24:25]
	v_add_co_u32_e32 v72, vcc, s74, v72
	v_add_f32_dpp v67, v67, v67 quad_perm:[1,0,3,2] row_mask:0xf bank_mask:0xf bound_ctrl:1
	s_nop 0
	v_addc_co_u32_e32 v73, vcc, 0, v73, vcc
	v_add_f32_dpp v67, v67, v67 quad_perm:[2,3,0,1] row_mask:0xf bank_mask:0xf bound_ctrl:1
	s_cmpk_gt_i32 s45, 0x3fff
	s_cselect_b64 s[58:59], -1, 0
	v_add_f32_dpp v67, v67, v67 row_half_mirror row_mask:0xf bank_mask:0xf bound_ctrl:1
	s_cmpk_lt_i32 s45, 0x4000
	s_nop 0
	v_add_f32_dpp v67, v67, v67 row_mirror row_mask:0xf bank_mask:0xf bound_ctrl:1
	v_mov_b32_e32 v74, v67
	s_nop 1
	v_permlane16_swap_b32_e32 v67, v74
	v_add_f32_e32 v67, v67, v74
	v_mov_b32_e32 v74, v67
	s_nop 1
	v_permlane32_swap_b32_e32 v67, v74
	v_add_f32_e32 v67, v67, v74
	v_fmamk_f32 v67, v67, 0x3b2aaaab, v47
	v_rsq_f32_e32 v74, v67
	s_nop 0
	v_pk_mul_f32 v[2:3], v[74:75], v[2:3] op_sel_hi:[0,1]
	v_pk_mul_f32 v[0:1], v[0:1], v[2:3]
	s_nop 0
	v_cvt_pk_bf16_f32 v0, v0, v1
	global_store_dword v[72:73], v0, off
	s_nop 0
	v_mov_b64_e32 v[0:1], v[92:93]
	v_pk_mul_f32 v[2:3], v[74:75], v[70:71] op_sel_hi:[0,1]
	v_pk_mul_f32 v[0:1], v[0:1], v[2:3]
	s_nop 0
	v_cvt_pk_bf16_f32 v0, v0, v1
	global_store_dword v[72:73], v0, off offset:256
	s_nop 0
	v_mov_b64_e32 v[0:1], v[94:95]
	v_pk_mul_f32 v[2:3], v[74:75], v[68:69] op_sel_hi:[0,1]
	v_lshlrev_b32_e32 v68, 16, v44
	v_and_b32_e32 v69, 0xffff0000, v44
	v_lshlrev_b32_e32 v44, 16, v45
	v_and_b32_e32 v45, 0xffff0000, v45
	v_mul_f32_e32 v67, v69, v69
	v_mul_f32_e32 v70, v45, v45
	v_fmac_f32_e32 v67, v68, v68
	v_fmac_f32_e32 v70, v44, v44
	v_add_f32_e32 v67, v67, v70
	v_pk_mul_f32 v[0:1], v[0:1], v[2:3]
	s_nop 0
	v_cvt_pk_bf16_f32 v0, v0, v1
	global_store_dword v[72:73], v0, off offset:512
	s_nop 0
	v_mov_b64_e32 v[0:1], v[96:97]
	v_mov_b64_e32 v[2:3], v[98:99]
	v_add_f32_dpp v67, v67, v67 quad_perm:[1,0,3,2] row_mask:0xf bank_mask:0xf bound_ctrl:1
	v_lshl_add_u64 v[72:73], s[8:9], 0, v[22:23]
	s_nop 0
	v_add_f32_dpp v67, v67, v67 quad_perm:[2,3,0,1] row_mask:0xf bank_mask:0xf bound_ctrl:1
	s_nop 1
	v_add_f32_dpp v67, v67, v67 row_half_mirror row_mask:0xf bank_mask:0xf bound_ctrl:1
	s_nop 1
	v_add_f32_dpp v67, v67, v67 row_mirror row_mask:0xf bank_mask:0xf bound_ctrl:1
	v_mov_b32_e32 v70, v67
	s_nop 1
	v_permlane16_swap_b32_e32 v67, v70
	v_add_f32_e32 v67, v67, v70
	v_mov_b32_e32 v70, v67
	s_nop 1
	v_permlane32_swap_b32_e32 v67, v70
	v_add_f32_e32 v67, v67, v70
	v_fmamk_f32 v67, v67, 0x3b800000, v47
	v_rsq_f32_e32 v70, v67
	s_nop 0
	v_pk_mul_f32 v[44:45], v[44:45], v[70:71] op_sel_hi:[1,0]
	v_pk_mul_f32 v[68:69], v[68:69], v[70:71] op_sel_hi:[1,0]
	s_waitcnt vmcnt(3)
	v_pk_mul_f32 v[2:3], v[2:3], v[44:45]
	v_pk_mul_f32 v[0:1], v[0:1], v[68:69]
	v_cvt_pk_bf16_f32 v45, v2, v3
	v_cvt_pk_bf16_f32 v44, v0, v1
	global_store_dwordx2 v[72:73], v[44:45], off
	s_cbranch_scc1 .LBB0_890
	s_mov_b64 s[62:63], 0
	s_cmpk_lt_u32 s45, 0x4080
	s_mov_b64 s[64:65], 0
	s_cbranch_scc0 .LBB0_891
	s_mov_b64 s[60:61], s[98:99]
	s_mov_b32 s55, s11
	s_lshl_b64 s[64:65], s[54:55], 10
	s_waitcnt lgkmcnt(0)
	s_add_u32 s47, s60, s64
	s_addc_u32 s49, s61, s65
	s_add_u32 s60, s47, 0x528a000
	s_addc_u32 s61, s49, 0
	s_mov_b64 s[64:65], -1
	s_branch .LBB0_891

; __device__ __forceinline__ void mla_prep(const Args& a, int vcu, int G, int lane, int wave) {
;     ...
;             if (m < MP) ((f32x4*)((float*)a.in[I_OUT + z] + O_CKV_P + (size_t)m * KVL))[lane] = kv;
;             else if (m < MP + NS) ((f32x4*)((float*)a.in[I_OUT + z] + O_CKV_S + (size_t)(m - MP) * KVL))[lane] = kv;
.LBB0_894:
	s_mov_b64 s[60:61], s[98:99]
	s_waitcnt lgkmcnt(0)
	s_add_u32 s47, s60, s26
	s_addc_u32 s49, s61, s27
	s_add_u32 s60, s47, s42
	s_addc_u32 s61, s49, s43

; __device__ __forceinline__ bf16 f2bf(float f) { return (bf16)(pk2(f, 0.f) & 0xffffu); }
; __device__ __forceinline__ void mla_prep(const Args& a, int vcu, int G, int lane, int wave) {
;     ...
;             if (lane < 16) {
;                 const float o1 = x1[qq] * cs[qq] - x2[qq] * sn4[qq], o2 = x1[qq] * sn4[qq] + x2[qq] * cs[qq];
;                 bf16* kr = (bf16*)(ws + WS_KR) + (size_t)m * ROPE;
;                 kr[lane] = f2bf(o1); kr[16 + lane] = f2bf(o2);
;                 float* ko = m < MP ? (float*)a.in[I_OUT + z] + O_KR_P + (size_t)m * ROPE : (m < MP + NS ? (float*)a.in[I_OUT + z] + O_KR_S + (size_t)(m - MP) * ROPE : nullptr);
;                 if (ko) { ko[lane] = o1; ko[16 + lane] = o2; }
.LBB0_896:
	v_lshlrev_b32_e32 v1, 16, v64
	v_lshlrev_b32_e32 v2, 16, v63
	v_mul_f32_e32 v0, v65, v1
	v_mul_f32_e32 v1, v66, v1
	v_fma_f32 v0, v66, v2, -v0
	v_fmac_f32_e32 v1, v65, v2
	v_lshl_add_u64 v[2:3], s[8:9], 0, v[20:21]
	v_add_co_u32_e32 v2, vcc, 0x1de00000, v2
	v_cvt_pk_bf16_f32 v44, v0, s0
	s_nop 0
	v_addc_co_u32_e32 v3, vcc, 0, v3, vcc
	global_store_short v[2:3], v44, off
	v_cvt_pk_bf16_f32 v44, v1, s0
	s_andn2_b64 vcc, exec, s[58:59]
	s_mov_b64 s[62:63], -1
	global_store_short v[2:3], v44, off offset:32
	s_cbranch_vccnz .LBB0_899
	s_mov_b64 s[62:63], 0
	s_cmpk_gt_u32 s45, 0x407f
	s_mov_b64 s[58:59], 0
	s_cbranch_scc1 .LBB0_899
	s_mov_b64 s[58:59], s[98:99]
	s_mov_b32 s55, s11
	s_lshl_b64 s[54:55], s[54:55], 7
	s_waitcnt lgkmcnt(0)
	s_add_u32 s45, s58, s54
	s_addc_u32 s47, s59, s55
	s_add_u32 s58, s45, 0x52aa000
	s_addc_u32 s59, s47, 0
.LBB0_899:
	s_andn2_b64 vcc, exec, s[62:63]
	s_cbranch_vccnz .LBB0_901
	s_mov_b64 s[54:55], s[98:99]
	s_waitcnt lgkmcnt(0)
	s_add_u32 s45, s54, s20
	s_addc_u32 s47, s55, s21
	s_add_u32 s58, s45, s40
	s_addc_u32 s59, s47, s41

; __device__ __forceinline__ float bflo(unsigned w) { return __uint_as_float(w << 16); }
; __device__ __forceinline__ float bfhi(unsigned w) { return __uint_as_float(w & 0xffff0000u); }
; __device__ __forceinline__ unsigned pk2(float lo, float hi) { f32x2 v = {lo, hi}; bf16x2_t b = __builtin_convertvector(v, bf16x2_t); return __builtin_bit_cast(unsigned, b); }
; __device__ __forceinline__ void mla_prep(const Args& a, int vcu, int G, int lane, int wave) {
;     ...
;         for (int qq = 0; qq < 4; ++qq) { const int m = m0 + qq * NGW; if (m >= MT) break;
;             float q[6]; float s = 0.f;
; #pragma unroll
;             for (int j = 0; j < 3; ++j) { const unsigned w = qw[qq][j]; q[2 * j] = bflo(w); q[2 * j + 1] = bfhi(w); s += q[2 * j] * q[2 * j] + q[2 * j + 1] * q[2 * j + 1]; }
;             const float rq = __builtin_amdgcn_rsqf(wave_sum(s) * (1.f / QL) + EPS);
; #pragma unroll
;             for (int j = 0; j < 3; ++j) { const f32x2 g = ((const f32x2*)qn)[lane + 64 * j]; ((unsigned*)((bf16*)(ws + WS_CQ) + (size_t)m * QL))[lane + 64 * j] = pk2(q[2 * j] * rq * g.x, q[2 * j + 1] * rq * g.y); }
;             const u32x2 kw = kw4[qq];
;             f32x4 kv = {bflo(kw.x), bfhi(kw.x), bflo(kw.y), bfhi(kw.y)};
;             const float rk = __builtin_amdgcn_rsqf(wave_sum((kv.x * kv.x + kv.y * kv.y) + (kv.z * kv.z + kv.w * kv.w)) * (1.f / KVL) + EPS);
;             kv = kv * rk * ((const f32x4*)kn)[lane];
;             { u32x2 o; o.x = pk2(kv.x, kv.y); o.y = pk2(kv.z, kv.w); ((u32x2*)((bf16*)(ws + WS_CKV) + (size_t)m * KVL))[lane] = o; }
;             if (m < MP) ((f32x4*)((float*)a.in[I_OUT + z] + O_CKV_P + (size_t)m * KVL))[lane] = kv;
;             else if (m < MP + NS) ((f32x4*)((float*)a.in[I_OUT + z] + O_CKV_S + (size_t)(m - MP) * KVL))[lane] = kv;
.LBB0_903:
	s_or_b64 exec, exec, s[60:61]
	s_andn2_b64 vcc, exec, s[56:57]
	s_cbranch_vccnz .LBB0_870
	v_mov_b64_e32 v[0:1], v[90:91]
	v_lshlrev_b32_e32 v2, 16, v60
	v_and_b32_e32 v3, 0xffff0000, v60
	v_lshlrev_b32_e32 v44, 16, v62
	v_and_b32_e32 v45, 0xffff0000, v62
	v_lshlrev_b32_e32 v60, 16, v61
	v_and_b32_e32 v61, 0xffff0000, v61
	v_pk_mul_f32 v[62:63], v[2:3], v[2:3]
	v_pk_mul_f32 v[64:65], v[44:45], v[44:45]
	v_pk_mul_f32 v[66:67], v[60:61], v[60:61]
	v_add_f32_e32 v64, v64, v65
	v_add_f32_e32 v62, v62, v63
	v_add_f32_e32 v63, v66, v67
	v_add_f32_e32 v62, v62, v64
	v_add_f32_e32 v62, v62, v63
	v_mad_i64_i32 v[64:65], s[54:55], s48, v48, v[16:17]
	s_nop 0
	v_add_f32_dpp v62, v62, v62 quad_perm:[1,0,3,2] row_mask:0xf bank_mask:0xf bound_ctrl:1
	s_ashr_i32 s49, s48, 31
	s_lshl_b64 s[54:55], s[48:49], 9
	v_add_f32_dpp v62, v62, v62 quad_perm:[2,3,0,1] row_mask:0xf bank_mask:0xf bound_ctrl:1
	s_cmpk_gt_i32 s48, 0x3fff
	s_nop 0
	v_add_f32_dpp v62, v62, v62 row_half_mirror row_mask:0xf bank_mask:0xf bound_ctrl:1
	s_nop 1
	v_add_f32_dpp v62, v62, v62 row_mirror row_mask:0xf bank_mask:0xf bound_ctrl:1
	v_mov_b32_e32 v63, v62
	s_nop 1
	v_permlane16_swap_b32_e32 v62, v63
	v_add_f32_e32 v62, v62, v63
	v_mov_b32_e32 v63, v62
	s_nop 1
	v_permlane32_swap_b32_e32 v62, v63
	v_add_f32_e32 v62, v62, v63
	v_fmamk_f32 v62, v62, 0x3b2aaaab, v47
	v_rsq_f32_e32 v62, v62
	s_nop 0
	v_pk_mul_f32 v[2:3], v[62:63], v[2:3] op_sel_hi:[0,1]
	v_pk_mul_f32 v[0:1], v[0:1], v[2:3]
	s_nop 0
	v_cvt_pk_bf16_f32 v0, v0, v1
	global_store_dword v[64:65], v0, off
	s_nop 0
	v_mov_b64_e32 v[0:1], v[92:93]
	v_pk_mul_f32 v[2:3], v[62:63], v[44:45] op_sel_hi:[0,1]
	v_lshlrev_b32_e32 v44, 16, v42
	v_and_b32_e32 v45, 0xffff0000, v42
	v_lshlrev_b32_e32 v42, 16, v43
	v_and_b32_e32 v43, 0xffff0000, v43
	v_pk_mul_f32 v[0:1], v[0:1], v[2:3]
	s_nop 0
	v_cvt_pk_bf16_f32 v0, v0, v1
	global_store_dword v[64:65], v0, off offset:256
	s_nop 0
	v_mov_b64_e32 v[0:1], v[94:95]
	v_pk_mul_f32 v[2:3], v[62:63], v[60:61] op_sel_hi:[0,1]
	v_mul_f32_e32 v60, v45, v45
	v_mul_f32_e32 v61, v43, v43
	v_fmac_f32_e32 v60, v44, v44
	v_fmac_f32_e32 v61, v42, v42
	v_add_f32_e32 v60, v60, v61
	v_lshl_add_u64 v[62:63], v[12:13], 0, s[54:55]
	s_cselect_b64 s[54:55], -1, 0
	v_add_f32_dpp v60, v60, v60 quad_perm:[1,0,3,2] row_mask:0xf bank_mask:0xf bound_ctrl:1
	s_cmpk_lt_i32 s48, 0x4000
	v_pk_mul_f32 v[0:1], v[0:1], v[2:3]
	s_nop 0
	v_cvt_pk_bf16_f32 v0, v0, v1
	global_store_dword v[64:65], v0, off offset:512
	s_nop 0
	v_mov_b64_e32 v[0:1], v[96:97]
	v_mov_b64_e32 v[2:3], v[98:99]
	v_add_f32_dpp v60, v60, v60 quad_perm:[2,3,0,1] row_mask:0xf bank_mask:0xf bound_ctrl:1
	s_nop 1
	v_add_f32_dpp v60, v60, v60 row_half_mirror row_mask:0xf bank_mask:0xf bound_ctrl:1
	s_nop 1
	v_add_f32_dpp v60, v60, v60 row_mirror row_mask:0xf bank_mask:0xf bound_ctrl:1
	v_mov_b32_e32 v61, v60
	s_nop 1
	v_permlane16_swap_b32_e32 v60, v61
	v_add_f32_e32 v60, v60, v61
	v_mov_b32_e32 v61, v60
	s_nop 1
	v_permlane32_swap_b32_e32 v60, v61
	v_add_f32_e32 v60, v60, v61
	v_fmamk_f32 v60, v60, 0x3b800000, v47
	v_rsq_f32_e32 v60, v60
	s_nop 0
	v_pk_mul_f32 v[42:43], v[42:43], v[60:61] op_sel_hi:[1,0]
	v_pk_mul_f32 v[44:45], v[44:45], v[60:61] op_sel_hi:[1,0]
	s_waitcnt vmcnt(3)
	v_pk_mul_f32 v[2:3], v[2:3], v[42:43]
	v_pk_mul_f32 v[0:1], v[0:1], v[44:45]
	v_cvt_pk_bf16_f32 v43, v2, v3
	v_cvt_pk_bf16_f32 v42, v0, v1
	global_store_dwordx2 v[62:63], v[42:43], off
	s_cbranch_scc1 .LBB0_907
	s_mov_b64 s[58:59], 0
	s_cmpk_lt_u32 s48, 0x4080
	s_mov_b64 s[60:61], 0
	s_cbranch_scc0 .LBB0_908
	s_mov_b64 s[56:57], s[98:99]
	s_mov_b32 s53, s11
	s_lshl_b64 s[60:61], s[52:53], 10
	s_waitcnt lgkmcnt(0)
	s_add_u32 s45, s56, s60
	s_addc_u32 s47, s57, s61
	s_add_u32 s56, s45, 0x528a000
	s_addc_u32 s57, s47, 0
	s_mov_b64 s[60:61], -1
	s_branch .LBB0_908

; __device__ __forceinline__ void mla_prep(const Args& a, int vcu, int G, int lane, int wave) {
;     ...
;             if (m < MP) ((f32x4*)((float*)a.in[I_OUT + z] + O_CKV_P + (size_t)m * KVL))[lane] = kv;
;             else if (m < MP + NS) ((f32x4*)((float*)a.in[I_OUT + z] + O_CKV_S + (size_t)(m - MP) * KVL))[lane] = kv;
.LBB0_911:
	s_mov_b64 s[56:57], s[98:99]
	s_lshl_b64 s[58:59], s[48:49], 8
	s_lshl_b64 s[58:59], s[58:59], 2
	s_waitcnt lgkmcnt(0)
	s_add_u32 s45, s56, s58
	s_addc_u32 s47, s57, s59
	s_add_u32 s56, s45, 0x4080000
	s_addc_u32 s57, s47, 0

; __device__ __forceinline__ bf16 f2bf(float f) { return (bf16)(pk2(f, 0.f) & 0xffffu); }
; __device__ __forceinline__ void mla_prep(const Args& a, int vcu, int G, int lane, int wave) {
;     ...
;             if (lane < 16) {
;                 const float o1 = x1[qq] * cs[qq] - x2[qq] * sn4[qq], o2 = x1[qq] * sn4[qq] + x2[qq] * cs[qq];
;                 bf16* kr = (bf16*)(ws + WS_KR) + (size_t)m * ROPE;
;                 kr[lane] = f2bf(o1); kr[16 + lane] = f2bf(o2);
;                 float* ko = m < MP ? (float*)a.in[I_OUT + z] + O_KR_P + (size_t)m * ROPE : (m < MP + NS ? (float*)a.in[I_OUT + z] + O_KR_S + (size_t)(m - MP) * ROPE : nullptr);
;                 if (ko) { ko[lane] = o1; ko[16 + lane] = o2; }
.LBB0_913:
	v_lshlrev_b32_e32 v1, 16, v59
	v_lshlrev_b32_e32 v2, 16, v58
	v_mul_f32_e32 v0, v56, v1
	v_fma_f32 v0, v57, v2, -v0
	v_mul_f32_e32 v1, v57, v1
	s_lshl_b64 s[58:59], s[48:49], 6
	v_fmac_f32_e32 v1, v56, v2
	v_cvt_pk_bf16_f32 v42, v0, s0
	v_lshl_add_u64 v[2:3], v[18:19], 0, s[58:59]
	global_store_short v[2:3], v42, off
	v_cvt_pk_bf16_f32 v42, v1, s0
	s_andn2_b64 vcc, exec, s[54:55]
	s_mov_b64 s[58:59], -1
	global_store_short v[2:3], v42, off offset:32
	s_cbranch_vccnz .LBB0_916
	s_mov_b64 s[58:59], 0
	s_cmpk_gt_u32 s48, 0x407f
	s_mov_b64 s[54:55], 0
	s_cbranch_scc1 .LBB0_916
	s_mov_b64 s[54:55], s[98:99]
	s_mov_b32 s53, s11
	s_lshl_b64 s[52:53], s[52:53], 7
	s_waitcnt lgkmcnt(0)
	s_add_u32 s45, s54, s52
	s_addc_u32 s47, s55, s53
	s_add_u32 s54, s45, 0x52aa000
	s_addc_u32 s55, s47, 0
.LBB0_916:
	s_andn2_b64 vcc, exec, s[58:59]
	s_cbranch_vccnz .LBB0_918
	s_mov_b64 s[52:53], s[98:99]
	s_lshl_b64 s[48:49], s[48:49], 5
	s_lshl_b64 s[48:49], s[48:49], 2
	s_waitcnt lgkmcnt(0)
	s_add_u32 s45, s52, s48
	s_addc_u32 s47, s53, s49
	s_add_u32 s54, s45, 0x5080000
	s_addc_u32 s55, s47, 0

; __device__ __forceinline__ float bflo(unsigned w) { return __uint_as_float(w << 16); }
; __device__ __forceinline__ float bfhi(unsigned w) { return __uint_as_float(w & 0xffff0000u); }
; __device__ __forceinline__ unsigned pk2(float lo, float hi) { f32x2 v = {lo, hi}; bf16x2_t b = __builtin_convertvector(v, bf16x2_t); return __builtin_bit_cast(unsigned, b); }
; __device__ __forceinline__ void mla_prep(const Args& a, int vcu, int G, int lane, int wave) {
;     ...
;         for (int qq = 0; qq < 4; ++qq) { const int m = m0 + qq * NGW; if (m >= MT) break;
;             float q[6]; float s = 0.f;
; #pragma unroll
;             for (int j = 0; j < 3; ++j) { const unsigned w = qw[qq][j]; q[2 * j] = bflo(w); q[2 * j + 1] = bfhi(w); s += q[2 * j] * q[2 * j] + q[2 * j + 1] * q[2 * j + 1]; }
;             const float rq = __builtin_amdgcn_rsqf(wave_sum(s) * (1.f / QL) + EPS);
; #pragma unroll
;             for (int j = 0; j < 3; ++j) { const f32x2 g = ((const f32x2*)qn)[lane + 64 * j]; ((unsigned*)((bf16*)(ws + WS_CQ) + (size_t)m * QL))[lane + 64 * j] = pk2(q[2 * j] * rq * g.x, q[2 * j + 1] * rq * g.y); }
;             const u32x2 kw = kw4[qq];
;             f32x4 kv = {bflo(kw.x), bfhi(kw.x), bflo(kw.y), bfhi(kw.y)};
;             const float rk = __builtin_amdgcn_rsqf(wave_sum((kv.x * kv.x + kv.y * kv.y) + (kv.z * kv.z + kv.w * kv.w)) * (1.f / KVL) + EPS);
;             kv = kv * rk * ((const f32x4*)kn)[lane];
;             { u32x2 o; o.x = pk2(kv.x, kv.y); o.y = pk2(kv.z, kv.w); ((u32x2*)((bf16*)(ws + WS_CKV) + (size_t)m * KVL))[lane] = o; }
;             if (m < MP) ((f32x4*)((float*)a.in[I_OUT + z] + O_CKV_P + (size_t)m * KVL))[lane] = kv;
;             else if (m < MP + NS) ((f32x4*)((float*)a.in[I_OUT + z] + O_CKV_S + (size_t)(m - MP) * KVL))[lane] = kv;
.LBB0_920:
	s_or_b64 exec, exec, s[56:57]
	s_andn2_b64 vcc, exec, s[50:51]
	s_cbranch_vccnz .LBB0_870
	v_mov_b64_e32 v[0:1], v[90:91]
	v_lshlrev_b32_e32 v2, 16, v53
	v_and_b32_e32 v3, 0xffff0000, v53
	v_lshlrev_b32_e32 v42, 16, v55
	v_and_b32_e32 v43, 0xffff0000, v55
	v_lshlrev_b32_e32 v44, 16, v54
	v_and_b32_e32 v45, 0xffff0000, v54
	v_pk_mul_f32 v[54:55], v[2:3], v[2:3]
	v_pk_mul_f32 v[56:57], v[42:43], v[42:43]
	v_pk_mul_f32 v[58:59], v[44:45], v[44:45]
	v_add_f32_e32 v53, v56, v57
	v_add_f32_e32 v54, v54, v55
	v_add_f32_e32 v55, v58, v59
	v_add_f32_e32 v53, v54, v53
	v_add_f32_e32 v53, v53, v55
	v_mad_i64_i32 v[56:57], s[48:49], s44, v48, v[16:17]
	s_nop 0
	v_add_f32_dpp v53, v53, v53 quad_perm:[1,0,3,2] row_mask:0xf bank_mask:0xf bound_ctrl:1
	s_ashr_i32 s45, s44, 31
	s_lshl_b64 s[48:49], s[44:45], 9
	v_add_f32_dpp v53, v53, v53 quad_perm:[2,3,0,1] row_mask:0xf bank_mask:0xf bound_ctrl:1
	s_cmpk_gt_i32 s44, 0x3fff
	s_nop 0
	v_add_f32_dpp v53, v53, v53 row_half_mirror row_mask:0xf bank_mask:0xf bound_ctrl:1
	s_nop 1
	v_add_f32_dpp v53, v53, v53 row_mirror row_mask:0xf bank_mask:0xf bound_ctrl:1
	v_mov_b32_e32 v54, v53
	s_nop 1
	v_permlane16_swap_b32_e32 v53, v54
	v_add_f32_e32 v53, v53, v54
	v_mov_b32_e32 v54, v53
	s_nop 1
	v_permlane32_swap_b32_e32 v53, v54
	v_add_f32_e32 v53, v53, v54
	v_fmamk_f32 v53, v53, 0x3b2aaaab, v47
	v_rsq_f32_e32 v54, v53
	s_nop 0
	v_pk_mul_f32 v[2:3], v[54:55], v[2:3] op_sel_hi:[0,1]
	v_pk_mul_f32 v[0:1], v[0:1], v[2:3]
	s_nop 0
	v_cvt_pk_bf16_f32 v0, v0, v1
	global_store_dword v[56:57], v0, off
	s_nop 0
	v_mov_b64_e32 v[0:1], v[92:93]
	v_pk_mul_f32 v[2:3], v[54:55], v[42:43] op_sel_hi:[0,1]
	v_lshlrev_b32_e32 v42, 16, v40
	v_and_b32_e32 v43, 0xffff0000, v40
	v_lshlrev_b32_e32 v40, 16, v41
	v_and_b32_e32 v41, 0xffff0000, v41
	v_pk_mul_f32 v[0:1], v[0:1], v[2:3]
	s_nop 0
	v_cvt_pk_bf16_f32 v0, v0, v1
	global_store_dword v[56:57], v0, off offset:256
	s_nop 0
	v_mov_b64_e32 v[0:1], v[94:95]
	v_pk_mul_f32 v[2:3], v[54:55], v[44:45] op_sel_hi:[0,1]
	v_mul_f32_e32 v44, v43, v43
	v_mul_f32_e32 v45, v41, v41
	v_fmac_f32_e32 v44, v42, v42
	v_fmac_f32_e32 v45, v40, v40
	v_add_f32_e32 v44, v44, v45
	v_lshl_add_u64 v[54:55], v[12:13], 0, s[48:49]
	s_cselect_b64 s[48:49], -1, 0
	v_add_f32_dpp v44, v44, v44 quad_perm:[1,0,3,2] row_mask:0xf bank_mask:0xf bound_ctrl:1
	s_cmpk_lt_i32 s44, 0x4000
	v_pk_mul_f32 v[0:1], v[0:1], v[2:3]
	s_nop 0
	v_cvt_pk_bf16_f32 v0, v0, v1
	global_store_dword v[56:57], v0, off offset:512
	s_nop 0
	v_mov_b64_e32 v[0:1], v[96:97]
	v_mov_b64_e32 v[2:3], v[98:99]
	v_add_f32_dpp v44, v44, v44 quad_perm:[2,3,0,1] row_mask:0xf bank_mask:0xf bound_ctrl:1
	s_nop 1
	v_add_f32_dpp v44, v44, v44 row_half_mirror row_mask:0xf bank_mask:0xf bound_ctrl:1
	s_nop 1
	v_add_f32_dpp v44, v44, v44 row_mirror row_mask:0xf bank_mask:0xf bound_ctrl:1
	v_mov_b32_e32 v45, v44
	s_nop 1
	v_permlane16_swap_b32_e32 v44, v45
	v_add_f32_e32 v44, v44, v45
	v_mov_b32_e32 v45, v44
	s_nop 1
	v_permlane32_swap_b32_e32 v44, v45
	v_add_f32_e32 v44, v44, v45
	v_fmamk_f32 v44, v44, 0x3b800000, v47
	v_rsq_f32_e32 v44, v44
	s_nop 0
	v_pk_mul_f32 v[40:41], v[40:41], v[44:45] op_sel_hi:[1,0]
	v_pk_mul_f32 v[42:43], v[42:43], v[44:45] op_sel_hi:[1,0]
	s_waitcnt vmcnt(3)
	v_pk_mul_f32 v[2:3], v[2:3], v[40:41]
	v_pk_mul_f32 v[0:1], v[0:1], v[42:43]
	v_cvt_pk_bf16_f32 v41, v2, v3
	v_cvt_pk_bf16_f32 v40, v0, v1
	global_store_dwordx2 v[54:55], v[40:41], off
	s_cbranch_scc1 .LBB0_924
	s_mov_b64 s[52:53], 0
	s_cmpk_lt_u32 s44, 0x4080
	s_mov_b64 s[54:55], 0
	s_cbranch_scc0 .LBB0_925
	s_mov_b64 s[50:51], s[98:99]
	s_mov_b32 s47, s11
	s_lshl_b64 s[54:55], s[46:47], 10
	s_waitcnt lgkmcnt(0)
	s_add_u32 s47, s50, s54
	s_addc_u32 s51, s51, s55
	s_add_u32 s50, s47, 0x528a000
	s_addc_u32 s51, s51, 0
	s_mov_b64 s[54:55], -1
	s_branch .LBB0_925

; __device__ __forceinline__ void mla_prep(const Args& a, int vcu, int G, int lane, int wave) {
;     ...
;             if (m < MP) ((f32x4*)((float*)a.in[I_OUT + z] + O_CKV_P + (size_t)m * KVL))[lane] = kv;
;             else if (m < MP + NS) ((f32x4*)((float*)a.in[I_OUT + z] + O_CKV_S + (size_t)(m - MP) * KVL))[lane] = kv;
.LBB0_928:
	s_mov_b64 s[50:51], s[98:99]
	s_lshl_b64 s[52:53], s[44:45], 8
	s_lshl_b64 s[52:53], s[52:53], 2
	s_waitcnt lgkmcnt(0)
	s_add_u32 s47, s50, s52
	s_addc_u32 s51, s51, s53
	s_add_u32 s50, s47, 0x4080000
	s_addc_u32 s51, s51, 0

; __device__ __forceinline__ bf16 f2bf(float f) { return (bf16)(pk2(f, 0.f) & 0xffffu); }
; __device__ __forceinline__ void mla_prep(const Args& a, int vcu, int G, int lane, int wave) {
;     ...
;             if (lane < 16) {
;                 const float o1 = x1[qq] * cs[qq] - x2[qq] * sn4[qq], o2 = x1[qq] * sn4[qq] + x2[qq] * cs[qq];
;                 bf16* kr = (bf16*)(ws + WS_KR) + (size_t)m * ROPE;
;                 kr[lane] = f2bf(o1); kr[16 + lane] = f2bf(o2);
;                 float* ko = m < MP ? (float*)a.in[I_OUT + z] + O_KR_P + (size_t)m * ROPE : (m < MP + NS ? (float*)a.in[I_OUT + z] + O_KR_S + (size_t)(m - MP) * ROPE : nullptr);
;                 if (ko) { ko[lane] = o1; ko[16 + lane] = o2; }
.LBB0_930:
	v_lshlrev_b32_e32 v1, 16, v52
	v_lshlrev_b32_e32 v2, 16, v51
	v_mul_f32_e32 v0, v49, v1
	v_fma_f32 v0, v50, v2, -v0
	v_mul_f32_e32 v1, v50, v1
	s_lshl_b64 s[52:53], s[44:45], 6
	v_fmac_f32_e32 v1, v49, v2
	v_cvt_pk_bf16_f32 v40, v0, s0
	v_lshl_add_u64 v[2:3], v[18:19], 0, s[52:53]
	global_store_short v[2:3], v40, off
	v_cvt_pk_bf16_f32 v40, v1, s0
	s_andn2_b64 vcc, exec, s[48:49]
	s_mov_b64 s[52:53], -1
	global_store_short v[2:3], v40, off offset:32
	s_cbranch_vccnz .LBB0_933
	s_mov_b64 s[52:53], 0
	s_cmpk_gt_u32 s44, 0x407f
	s_mov_b64 s[48:49], 0
	s_cbranch_scc1 .LBB0_933
	s_mov_b64 s[48:49], s[98:99]
	s_mov_b32 s47, s11
	s_lshl_b64 s[46:47], s[46:47], 7
	s_waitcnt lgkmcnt(0)
	s_add_u32 s46, s48, s46
	s_addc_u32 s47, s49, s47
	s_add_u32 s48, s46, 0x52aa000
	s_addc_u32 s49, s47, 0
.LBB0_933:
	s_andn2_b64 vcc, exec, s[52:53]
	s_cbranch_vccnz .LBB0_935
	s_mov_b64 s[46:47], s[98:99]
	s_lshl_b64 s[44:45], s[44:45], 5
	s_lshl_b64 s[44:45], s[44:45], 2
	s_waitcnt lgkmcnt(0)
	s_add_u32 s44, s46, s44
	s_addc_u32 s45, s47, s45
	s_add_u32 s48, s44, 0x5080000
	s_addc_u32 s49, s45, 0
